# LRU epilogue math: two independent (t,j) chains interleaved, v_sqrt_f32 instead of the refined sqrt expansion
# speedup vs baseline: 1.0156x; 1.0030x over previous
; #define LAS __attribute__((address_space(3)))
; __device__ __forceinline__ void lru_job(const bf16_t* P, bf16_t* Y, int l, int b, int kb, LAS float* lds, int wave_s) {
;     ...
;         for (int tt = 0; tt < 8; ++tt) { const int t = tg * 8 + tt; f32x2_t dd = {ba, bx};
; #pragma unroll
;             for (int i4 = 0; i4 < 16; ++i4) { const f32x4 xv = *(const LAS f32x4*)(XC + t * 64 + 4 * i4);
; #pragma unroll
;                 for (int q = 0; q < 4; ++q) { const f32x2_t xb = {xv[q], xv[q]}; dd = __builtin_elementwise_fma(xb, wax[4 * i4 + q], dd); } }
.LBB0_242:
	ds_read_b128 v[40:43], v99
	ds_read_b128 v[56:59], v99 offset:4096
	ds_read_b128 v[44:47], v99 offset:16
	ds_read_b128 v[60:63], v99 offset:4112
	ds_read_b128 v[48:51], v99 offset:32
	ds_read_b128 v[64:67], v99 offset:4128
	ds_read_b128 v[52:55], v99 offset:48
	ds_read_b128 v[68:71], v99 offset:4144
	ds_read_b32 v88, v100
	ds_read_b32 v89, v100 offset:256
	ds_read_b32 v90, v100 offset:512
	ds_read_b32 v91, v100 offset:768
	ds_read_b32 v92, v100 offset:4096
	ds_read_b32 v93, v100 offset:4352
	ds_read_b32 v94, v100 offset:4608
	ds_read_b32 v95, v100 offset:4864
	v_mov_b32_e32 v72, v96
	v_mov_b32_e32 v73, v96
	v_mov_b32_e32 v74, v96
	v_mov_b32_e32 v75, v96
	v_mov_b32_e32 v76, v97
	v_mov_b32_e32 v77, v97
	v_mov_b32_e32 v78, v97
	v_mov_b32_e32 v79, v97
	v_mov_b32_e32 v80, v96
	v_mov_b32_e32 v81, v96
	v_mov_b32_e32 v82, v96
	v_mov_b32_e32 v83, v96
	v_mov_b32_e32 v84, v97
	v_mov_b32_e32 v85, v97
	v_mov_b32_e32 v86, v97
	v_mov_b32_e32 v87, v97
	s_waitcnt lgkmcnt(14)
	s_nop 1
	v_mfma_f32_16x16x4_f32 v[72:75], v40, v0, v[72:75]
	v_mfma_f32_16x16x4_f32 v[76:79], v40, v16, v[76:79]
	v_mfma_f32_16x16x4_f32 v[80:83], v56, v0, v[80:83]
	v_mfma_f32_16x16x4_f32 v[84:87], v56, v16, v[84:87]
	v_mfma_f32_16x16x4_f32 v[72:75], v41, v1, v[72:75]
	v_mfma_f32_16x16x4_f32 v[76:79], v41, v17, v[76:79]
	v_mfma_f32_16x16x4_f32 v[80:83], v57, v1, v[80:83]
	v_mfma_f32_16x16x4_f32 v[84:87], v57, v17, v[84:87]
	v_mfma_f32_16x16x4_f32 v[72:75], v42, v2, v[72:75]
	v_mfma_f32_16x16x4_f32 v[76:79], v42, v18, v[76:79]
	v_mfma_f32_16x16x4_f32 v[80:83], v58, v2, v[80:83]
	v_mfma_f32_16x16x4_f32 v[84:87], v58, v18, v[84:87]
	v_mfma_f32_16x16x4_f32 v[72:75], v43, v3, v[72:75]
	v_mfma_f32_16x16x4_f32 v[76:79], v43, v19, v[76:79]
	v_mfma_f32_16x16x4_f32 v[80:83], v59, v3, v[80:83]
	v_mfma_f32_16x16x4_f32 v[84:87], v59, v19, v[84:87]
	s_waitcnt lgkmcnt(12)
	v_mfma_f32_16x16x4_f32 v[72:75], v44, v4, v[72:75]
	v_mfma_f32_16x16x4_f32 v[76:79], v44, v20, v[76:79]
	v_mfma_f32_16x16x4_f32 v[80:83], v60, v4, v[80:83]
	v_mfma_f32_16x16x4_f32 v[84:87], v60, v20, v[84:87]
	v_mfma_f32_16x16x4_f32 v[72:75], v45, v5, v[72:75]
	v_mfma_f32_16x16x4_f32 v[76:79], v45, v21, v[76:79]
	v_mfma_f32_16x16x4_f32 v[80:83], v61, v5, v[80:83]
	v_mfma_f32_16x16x4_f32 v[84:87], v61, v21, v[84:87]
	v_mfma_f32_16x16x4_f32 v[72:75], v46, v6, v[72:75]
	v_mfma_f32_16x16x4_f32 v[76:79], v46, v22, v[76:79]
	v_mfma_f32_16x16x4_f32 v[80:83], v62, v6, v[80:83]
	v_mfma_f32_16x16x4_f32 v[84:87], v62, v22, v[84:87]
	v_mfma_f32_16x16x4_f32 v[72:75], v47, v7, v[72:75]
	v_mfma_f32_16x16x4_f32 v[76:79], v47, v23, v[76:79]
	v_mfma_f32_16x16x4_f32 v[80:83], v63, v7, v[80:83]
	v_mfma_f32_16x16x4_f32 v[84:87], v63, v23, v[84:87]
	s_waitcnt lgkmcnt(10)
	v_mfma_f32_16x16x4_f32 v[72:75], v48, v8, v[72:75]
	v_mfma_f32_16x16x4_f32 v[76:79], v48, v24, v[76:79]
	v_mfma_f32_16x16x4_f32 v[80:83], v64, v8, v[80:83]
	v_mfma_f32_16x16x4_f32 v[84:87], v64, v24, v[84:87]
	v_mfma_f32_16x16x4_f32 v[72:75], v49, v9, v[72:75]
	v_mfma_f32_16x16x4_f32 v[76:79], v49, v25, v[76:79]
	v_mfma_f32_16x16x4_f32 v[80:83], v65, v9, v[80:83]
	v_mfma_f32_16x16x4_f32 v[84:87], v65, v25, v[84:87]
	v_mfma_f32_16x16x4_f32 v[72:75], v50, v10, v[72:75]
	v_mfma_f32_16x16x4_f32 v[76:79], v50, v26, v[76:79]
	v_mfma_f32_16x16x4_f32 v[80:83], v66, v10, v[80:83]
	v_mfma_f32_16x16x4_f32 v[84:87], v66, v26, v[84:87]
	v_mfma_f32_16x16x4_f32 v[72:75], v51, v11, v[72:75]
	v_mfma_f32_16x16x4_f32 v[76:79], v51, v27, v[76:79]
	v_mfma_f32_16x16x4_f32 v[80:83], v67, v11, v[80:83]
	v_mfma_f32_16x16x4_f32 v[84:87], v67, v27, v[84:87]
	s_waitcnt lgkmcnt(8)
	v_mfma_f32_16x16x4_f32 v[72:75], v52, v12, v[72:75]
	v_mfma_f32_16x16x4_f32 v[76:79], v52, v28, v[76:79]
	v_mfma_f32_16x16x4_f32 v[80:83], v68, v12, v[80:83]
	v_mfma_f32_16x16x4_f32 v[84:87], v68, v28, v[84:87]
	v_mfma_f32_16x16x4_f32 v[72:75], v53, v13, v[72:75]
	v_mfma_f32_16x16x4_f32 v[76:79], v53, v29, v[76:79]
	v_mfma_f32_16x16x4_f32 v[80:83], v69, v13, v[80:83]
	v_mfma_f32_16x16x4_f32 v[84:87], v69, v29, v[84:87]
	v_mfma_f32_16x16x4_f32 v[72:75], v54, v14, v[72:75]
	v_mfma_f32_16x16x4_f32 v[76:79], v54, v30, v[76:79]
	v_mfma_f32_16x16x4_f32 v[80:83], v70, v14, v[80:83]
	v_mfma_f32_16x16x4_f32 v[84:87], v70, v30, v[84:87]
	v_mfma_f32_16x16x4_f32 v[72:75], v55, v15, v[72:75]
	v_mfma_f32_16x16x4_f32 v[76:79], v55, v31, v[76:79]
	v_mfma_f32_16x16x4_f32 v[80:83], v71, v15, v[80:83]
	v_mfma_f32_16x16x4_f32 v[84:87], v71, v31, v[84:87]
	s_waitcnt lgkmcnt(0)
; __device__ __forceinline__ float sigmoidf_(float x) { return __builtin_amdgcn_rcpf(1.f + __expf(-x)); }
; __device__ __forceinline__ void lru_job(const bf16_t* P, bf16_t* Y, int l, int b, int kb, LAS float* lds, int wave_s) {
;     ...
;             const float rg = sigmoidf_(dd.x), ig = sigmoidf_(dd.y);
;             const float la = -8.f * rg * spl;
;             const float av = __expf(la);
;             Aa[t * 64 + j] = av;
;             Uu[t * 64 + j] = sqrtf(fmaxf(1.f - av * av, 0.f)) * (ig * XC[t * 64 + j]); }
;         __syncthreads();
	s_nop 7
	s_nop 3
	v_mul_f32_e32 v101, 0xbfb8aa3b, v72
	v_mul_f32_e32 v104, 0xbfb8aa3b, v73
	v_exp_f32_e32 v101, v101
	v_exp_f32_e32 v104, v104
	v_mul_f32_e32 v102, 0xbfb8aa3b, v76
	v_mul_f32_e32 v105, 0xbfb8aa3b, v77
	v_exp_f32_e32 v102, v102
	v_exp_f32_e32 v105, v105
	v_add_f32_e32 v101, 1.0, v101
	v_add_f32_e32 v104, 1.0, v104
	v_rcp_f32_e32 v101, v101
	v_rcp_f32_e32 v104, v104
	v_add_f32_e32 v102, 1.0, v102
	v_add_f32_e32 v105, 1.0, v105
	v_rcp_f32_e32 v102, v102
	v_rcp_f32_e32 v105, v105
	v_mul_f32_e32 v101, 0xc1000000, v101
	v_mul_f32_e32 v104, 0xc1000000, v104
	v_mul_f32_e32 v101, v98, v101
	v_mul_f32_e32 v104, v98, v104
	v_mul_f32_e32 v101, 0x3fb8aa3b, v101
	v_mul_f32_e32 v104, 0x3fb8aa3b, v104
	v_exp_f32_e32 v101, v101
	v_exp_f32_e32 v104, v104
	v_mul_f32_e32 v102, v88, v102
	v_mul_f32_e32 v105, v89, v105
	v_fma_f32 v103, -v101, v101, 1.0
	v_fma_f32 v106, -v104, v104, 1.0
	v_max_f32_e32 v103, 0, v103
	v_max_f32_e32 v106, 0, v106
	v_sqrt_f32_e32 v103, v103
	v_sqrt_f32_e32 v106, v106
	s_nop 0
	s_nop 0
	v_mul_f32_e32 v102, v102, v103
	v_mul_f32_e32 v105, v105, v106
	ds_write2st64_b32 v100, v101, v102 offset0:64 offset1:128
	ds_write2st64_b32 v100, v104, v105 offset0:65 offset1:129
	v_mul_f32_e32 v101, 0xbfb8aa3b, v74
	v_mul_f32_e32 v104, 0xbfb8aa3b, v75
	v_exp_f32_e32 v101, v101
	v_exp_f32_e32 v104, v104
	v_mul_f32_e32 v102, 0xbfb8aa3b, v78
	v_mul_f32_e32 v105, 0xbfb8aa3b, v79
	v_exp_f32_e32 v102, v102
	v_exp_f32_e32 v105, v105
	v_add_f32_e32 v101, 1.0, v101
	v_add_f32_e32 v104, 1.0, v104
	v_rcp_f32_e32 v101, v101
	v_rcp_f32_e32 v104, v104
	v_add_f32_e32 v102, 1.0, v102
	v_add_f32_e32 v105, 1.0, v105
	v_rcp_f32_e32 v102, v102
	v_rcp_f32_e32 v105, v105
	v_mul_f32_e32 v101, 0xc1000000, v101
	v_mul_f32_e32 v104, 0xc1000000, v104
	v_mul_f32_e32 v101, v98, v101
	v_mul_f32_e32 v104, v98, v104
	v_mul_f32_e32 v101, 0x3fb8aa3b, v101
	v_mul_f32_e32 v104, 0x3fb8aa3b, v104
	v_exp_f32_e32 v101, v101
	v_exp_f32_e32 v104, v104
	v_mul_f32_e32 v102, v90, v102
	v_mul_f32_e32 v105, v91, v105
	v_fma_f32 v103, -v101, v101, 1.0
	v_fma_f32 v106, -v104, v104, 1.0
	v_max_f32_e32 v103, 0, v103
	v_max_f32_e32 v106, 0, v106
	v_sqrt_f32_e32 v103, v103
	v_sqrt_f32_e32 v106, v106
	s_nop 0
	s_nop 0
	v_mul_f32_e32 v102, v102, v103
	v_mul_f32_e32 v105, v105, v106
	ds_write2st64_b32 v100, v101, v102 offset0:66 offset1:130
	ds_write2st64_b32 v100, v104, v105 offset0:67 offset1:131
	v_mul_f32_e32 v101, 0xbfb8aa3b, v80
	v_mul_f32_e32 v104, 0xbfb8aa3b, v81
	v_exp_f32_e32 v101, v101
	v_exp_f32_e32 v104, v104
	v_mul_f32_e32 v102, 0xbfb8aa3b, v84
	v_mul_f32_e32 v105, 0xbfb8aa3b, v85
	v_exp_f32_e32 v102, v102
	v_exp_f32_e32 v105, v105
	v_add_f32_e32 v101, 1.0, v101
	v_add_f32_e32 v104, 1.0, v104
	v_rcp_f32_e32 v101, v101
	v_rcp_f32_e32 v104, v104
	v_add_f32_e32 v102, 1.0, v102
	v_add_f32_e32 v105, 1.0, v105
	v_rcp_f32_e32 v102, v102
	v_rcp_f32_e32 v105, v105
	v_mul_f32_e32 v101, 0xc1000000, v101
	v_mul_f32_e32 v104, 0xc1000000, v104
	v_mul_f32_e32 v101, v98, v101
	v_mul_f32_e32 v104, v98, v104
	v_mul_f32_e32 v101, 0x3fb8aa3b, v101
	v_mul_f32_e32 v104, 0x3fb8aa3b, v104
	v_exp_f32_e32 v101, v101
	v_exp_f32_e32 v104, v104
	v_mul_f32_e32 v102, v92, v102
	v_mul_f32_e32 v105, v93, v105
	v_fma_f32 v103, -v101, v101, 1.0
	v_fma_f32 v106, -v104, v104, 1.0
	v_max_f32_e32 v103, 0, v103
	v_max_f32_e32 v106, 0, v106
	v_sqrt_f32_e32 v103, v103
	v_sqrt_f32_e32 v106, v106
	s_nop 0
	s_nop 0
	v_mul_f32_e32 v102, v102, v103
	v_mul_f32_e32 v105, v105, v106
	ds_write2st64_b32 v100, v101, v102 offset0:80 offset1:144
	ds_write2st64_b32 v100, v104, v105 offset0:81 offset1:145
	v_mul_f32_e32 v101, 0xbfb8aa3b, v82
	v_mul_f32_e32 v104, 0xbfb8aa3b, v83
	v_exp_f32_e32 v101, v101
	v_exp_f32_e32 v104, v104
	v_mul_f32_e32 v102, 0xbfb8aa3b, v86
	v_mul_f32_e32 v105, 0xbfb8aa3b, v87
	v_exp_f32_e32 v102, v102
	v_exp_f32_e32 v105, v105
	v_add_f32_e32 v101, 1.0, v101
	v_add_f32_e32 v104, 1.0, v104
	v_rcp_f32_e32 v101, v101
	v_rcp_f32_e32 v104, v104
	v_add_f32_e32 v102, 1.0, v102
	v_add_f32_e32 v105, 1.0, v105
	v_rcp_f32_e32 v102, v102
	v_rcp_f32_e32 v105, v105
	v_mul_f32_e32 v101, 0xc1000000, v101
	v_mul_f32_e32 v104, 0xc1000000, v104
	v_mul_f32_e32 v101, v98, v101
	v_mul_f32_e32 v104, v98, v104
	v_mul_f32_e32 v101, 0x3fb8aa3b, v101
	v_mul_f32_e32 v104, 0x3fb8aa3b, v104
	v_exp_f32_e32 v101, v101
	v_exp_f32_e32 v104, v104
	v_mul_f32_e32 v102, v94, v102
	v_mul_f32_e32 v105, v95, v105
	v_fma_f32 v103, -v101, v101, 1.0
	v_fma_f32 v106, -v104, v104, 1.0
	v_max_f32_e32 v103, 0, v103
	v_max_f32_e32 v106, 0, v106
	v_sqrt_f32_e32 v103, v103
	v_sqrt_f32_e32 v106, v106
	s_nop 0
	s_nop 0
	v_mul_f32_e32 v102, v102, v103
	v_mul_f32_e32 v105, v105, v106
	ds_write2st64_b32 v100, v101, v102 offset0:82 offset1:146
	ds_write2st64_b32 v100, v104, v105 offset0:83 offset1:147
	s_waitcnt lgkmcnt(0)
	s_barrier
	s_and_saveexec_b64 s[4:5], vcc
	s_cbranch_execz .LBB0_239
; __device__ __forceinline__ void lru_job(const bf16_t* P, bf16_t* Y, int l, int b, int kb, LAS float* lds, int wave_s) {
;     ...
;         if (tid < 64) {
;             for (int tb = 0; tb < TC; tb += 8) { float av[8], uv[8];
; #pragma unroll
;                 for (int k = 0; k < 8; ++k) { av[k] = Aa[(tb + k) * 64 + j]; uv[k] = Uu[(tb + k) * 64 + j]; }
; #pragma unroll
;                 for (int k = 0; k < 8; ++k) { hs = av[k] * hs + uv[k]; Hh[(tb + k) * 64 + j] = hs; } }
;         }
	ds_read2st64_b32 v[216:217], v177 offset0:128 offset1:129
	ds_read2st64_b32 v[218:219], v177 offset0:64 offset1:65
	ds_read2st64_b32 v[220:221], v177 offset0:66 offset1:67
	ds_read2st64_b32 v[222:223], v177 offset0:68 offset1:69
	ds_read2st64_b32 v[224:225], v177 offset0:70 offset1:71
	ds_read2st64_b32 v[226:227], v177 offset0:130 offset1:131
	ds_read2st64_b32 v[228:229], v177 offset0:132 offset1:133
	ds_read2st64_b32 v[230:231], v177 offset0:134 offset1:135
	s_waitcnt lgkmcnt(6)
	v_fma_f32 v134, v135, v218, v216
	v_fmac_f32_e32 v217, v134, v219
	ds_write2st64_b32 v177, v134, v217 offset0:192 offset1:193
	s_waitcnt lgkmcnt(3)
	v_fma_f32 v134, v217, v220, v226
	v_fmac_f32_e32 v227, v134, v221
	ds_write2st64_b32 v177, v134, v227 offset0:194 offset1:195
	s_waitcnt lgkmcnt(3)
	v_fma_f32 v134, v227, v222, v228
	v_fmac_f32_e32 v229, v134, v223
	ds_write2st64_b32 v177, v134, v229 offset0:196 offset1:197
	s_waitcnt lgkmcnt(3)
	v_fma_f32 v134, v229, v224, v230
	v_fmac_f32_e32 v231, v134, v225
	ds_write2st64_b32 v177, v134, v231 offset0:198 offset1:199
	ds_read2st64_b32 v[134:135], v177 offset0:136 offset1:137
	ds_read2st64_b32 v[216:217], v177 offset0:72 offset1:73
	ds_read2st64_b32 v[218:219], v177 offset0:74 offset1:75
	ds_read2st64_b32 v[220:221], v177 offset0:76 offset1:77
	ds_read2st64_b32 v[222:223], v177 offset0:78 offset1:79
	ds_read2st64_b32 v[224:225], v177 offset0:138 offset1:139
	ds_read2st64_b32 v[226:227], v177 offset0:140 offset1:141
	ds_read2st64_b32 v[228:229], v177 offset0:142 offset1:143
	s_waitcnt lgkmcnt(6)
	v_fma_f32 v134, v231, v216, v134
	v_fmac_f32_e32 v135, v134, v217
	ds_write2st64_b32 v177, v134, v135 offset0:200 offset1:201
	s_waitcnt lgkmcnt(3)
	v_fma_f32 v134, v135, v218, v224
	v_fmac_f32_e32 v225, v134, v219
	ds_write2st64_b32 v177, v134, v225 offset0:202 offset1:203
	s_waitcnt lgkmcnt(3)
	v_fma_f32 v134, v225, v220, v226
	v_fmac_f32_e32 v227, v134, v221
	ds_write2st64_b32 v177, v134, v227 offset0:204 offset1:205
	s_waitcnt lgkmcnt(3)
	v_fma_f32 v134, v227, v222, v228
	v_fmac_f32_e32 v229, v134, v223
	ds_write2st64_b32 v177, v134, v229 offset0:206 offset1:207
	ds_read2st64_b32 v[134:135], v177 offset0:144 offset1:145
	ds_read2st64_b32 v[216:217], v177 offset0:80 offset1:81
	ds_read2st64_b32 v[218:219], v177 offset0:82 offset1:83
	ds_read2st64_b32 v[220:221], v177 offset0:84 offset1:85
	ds_read2st64_b32 v[222:223], v177 offset0:86 offset1:87
	ds_read2st64_b32 v[224:225], v177 offset0:146 offset1:147
	ds_read2st64_b32 v[226:227], v177 offset0:148 offset1:149
	ds_read2st64_b32 v[230:231], v177 offset0:150 offset1:151
	s_waitcnt lgkmcnt(6)
	v_fma_f32 v134, v229, v216, v134
	v_fmac_f32_e32 v135, v134, v217
	ds_write2st64_b32 v177, v134, v135 offset0:208 offset1:209
	s_waitcnt lgkmcnt(3)
	v_fma_f32 v134, v135, v218, v224
	v_fmac_f32_e32 v225, v134, v219
	ds_write2st64_b32 v177, v134, v225 offset0:210 offset1:211
	s_waitcnt lgkmcnt(3)
	v_fma_f32 v134, v225, v220, v226
	v_fmac_f32_e32 v227, v134, v221
	ds_write2st64_b32 v177, v134, v227 offset0:212 offset1:213
	s_waitcnt lgkmcnt(3)
	v_fma_f32 v134, v227, v222, v230
	v_fmac_f32_e32 v231, v134, v223
	ds_write2st64_b32 v177, v134, v231 offset0:214 offset1:215
	ds_read2st64_b32 v[134:135], v177 offset0:152 offset1:153
	ds_read2st64_b32 v[216:217], v177 offset0:88 offset1:89
	ds_read2st64_b32 v[218:219], v177 offset0:90 offset1:91
	ds_read2st64_b32 v[220:221], v177 offset0:92 offset1:93
	ds_read2st64_b32 v[222:223], v177 offset0:94 offset1:95
	ds_read2st64_b32 v[224:225], v177 offset0:154 offset1:155
	ds_read2st64_b32 v[226:227], v177 offset0:156 offset1:157
	ds_read2st64_b32 v[228:229], v177 offset0:158 offset1:159
	s_waitcnt lgkmcnt(6)
	v_fma_f32 v134, v231, v216, v134
	v_fmac_f32_e32 v135, v134, v217
	ds_write2st64_b32 v177, v134, v135 offset0:216 offset1:217
	s_waitcnt lgkmcnt(3)
	v_fma_f32 v134, v135, v218, v224
	v_fmac_f32_e32 v225, v134, v219
	ds_write2st64_b32 v177, v134, v225 offset0:218 offset1:219
	s_waitcnt lgkmcnt(3)
	v_fma_f32 v134, v225, v220, v226
	v_fmac_f32_e32 v227, v134, v221
	ds_write2st64_b32 v177, v134, v227 offset0:220 offset1:221
	s_waitcnt lgkmcnt(3)
; __device__ __forceinline__ void lru_job(const bf16_t* P, bf16_t* Y, int l, int b, int kb, LAS float* lds, int wave_s) {
;     ...
;         if (tid < 64) {
;             for (int tb = 0; tb < TC; tb += 8) { float av[8], uv[8];
; #pragma unroll
;                 for (int k = 0; k < 8; ++k) { av[k] = Aa[(tb + k) * 64 + j]; uv[k] = Uu[(tb + k) * 64 + j]; }
; #pragma unroll
;                 for (int k = 0; k < 8; ++k) { hs = av[k] * hs + uv[k]; Hh[(tb + k) * 64 + j] = hs; } }
;         }
	v_fma_f32 v134, v227, v222, v228
	v_fmac_f32_e32 v229, v134, v223
	ds_write2st64_b32 v177, v134, v229 offset0:222 offset1:223
	ds_read2st64_b32 v[134:135], v177 offset0:160 offset1:161
	ds_read2st64_b32 v[216:217], v177 offset0:96 offset1:97
	ds_read2st64_b32 v[218:219], v177 offset0:98 offset1:99
	ds_read2st64_b32 v[220:221], v177 offset0:100 offset1:101
	ds_read2st64_b32 v[222:223], v177 offset0:102 offset1:103
	ds_read2st64_b32 v[224:225], v177 offset0:162 offset1:163
	ds_read2st64_b32 v[226:227], v177 offset0:164 offset1:165
	ds_read2st64_b32 v[230:231], v177 offset0:166 offset1:167
	s_waitcnt lgkmcnt(6)
	v_fma_f32 v134, v229, v216, v134
	v_fmac_f32_e32 v135, v134, v217
	ds_write2st64_b32 v177, v134, v135 offset0:224 offset1:225
	s_waitcnt lgkmcnt(3)
	v_fma_f32 v134, v135, v218, v224
	v_fmac_f32_e32 v225, v134, v219
	ds_write2st64_b32 v177, v134, v225 offset0:226 offset1:227
	s_waitcnt lgkmcnt(3)
	v_fma_f32 v134, v225, v220, v226
	v_fmac_f32_e32 v227, v134, v221
	ds_write2st64_b32 v177, v134, v227 offset0:228 offset1:229
	s_waitcnt lgkmcnt(3)
	v_fma_f32 v134, v227, v222, v230
	v_fmac_f32_e32 v231, v134, v223
	ds_write2st64_b32 v177, v134, v231 offset0:230 offset1:231
	ds_read2st64_b32 v[134:135], v177 offset0:168 offset1:169
	ds_read2st64_b32 v[216:217], v177 offset0:104 offset1:105
	ds_read2st64_b32 v[218:219], v177 offset0:106 offset1:107
	ds_read2st64_b32 v[220:221], v177 offset0:108 offset1:109
	ds_read2st64_b32 v[222:223], v177 offset0:110 offset1:111
	ds_read2st64_b32 v[224:225], v177 offset0:170 offset1:171
	ds_read2st64_b32 v[226:227], v177 offset0:172 offset1:173
	ds_read2st64_b32 v[228:229], v177 offset0:174 offset1:175
	s_waitcnt lgkmcnt(6)
	v_fma_f32 v134, v231, v216, v134
	v_fmac_f32_e32 v135, v134, v217
	ds_write2st64_b32 v177, v134, v135 offset0:232 offset1:233
	s_waitcnt lgkmcnt(3)
	v_fma_f32 v134, v135, v218, v224
	v_fmac_f32_e32 v225, v134, v219
	ds_write2st64_b32 v177, v134, v225 offset0:234 offset1:235
	s_waitcnt lgkmcnt(3)
	v_fma_f32 v134, v225, v220, v226
	v_fmac_f32_e32 v227, v134, v221
	ds_write2st64_b32 v177, v134, v227 offset0:236 offset1:237
	s_waitcnt lgkmcnt(3)
	v_fma_f32 v134, v227, v222, v228
	v_fmac_f32_e32 v229, v134, v223
	ds_write2st64_b32 v177, v134, v229 offset0:238 offset1:239
	ds_read2st64_b32 v[134:135], v177 offset0:176 offset1:177
	ds_read2st64_b32 v[216:217], v177 offset0:112 offset1:113
	ds_read2st64_b32 v[218:219], v177 offset0:114 offset1:115
	ds_read2st64_b32 v[220:221], v177 offset0:116 offset1:117
	ds_read2st64_b32 v[222:223], v177 offset0:118 offset1:119
	ds_read2st64_b32 v[224:225], v177 offset0:178 offset1:179
	ds_read2st64_b32 v[226:227], v177 offset0:180 offset1:181
	ds_read2st64_b32 v[230:231], v177 offset0:182 offset1:183
	s_waitcnt lgkmcnt(6)
	v_fma_f32 v134, v229, v216, v134
	v_fmac_f32_e32 v135, v134, v217
	ds_write2st64_b32 v177, v134, v135 offset0:240 offset1:241
	s_waitcnt lgkmcnt(3)
	v_fma_f32 v134, v135, v218, v224
	v_fmac_f32_e32 v225, v134, v219
	ds_write2st64_b32 v177, v134, v225 offset0:242 offset1:243
	s_waitcnt lgkmcnt(3)
	v_fma_f32 v134, v225, v220, v226
	v_fmac_f32_e32 v227, v134, v221
	ds_write2st64_b32 v177, v134, v227 offset0:244 offset1:245
	s_waitcnt lgkmcnt(3)
	v_fma_f32 v134, v227, v222, v230
	v_fmac_f32_e32 v231, v134, v223
	ds_write2st64_b32 v177, v134, v231 offset0:246 offset1:247
	ds_read2st64_b32 v[216:217], v177 offset0:184 offset1:185
	ds_read2st64_b32 v[218:219], v177 offset0:120 offset1:121
	ds_read2st64_b32 v[220:221], v177 offset0:122 offset1:123
	ds_read2st64_b32 v[222:223], v177 offset0:124 offset1:125
	ds_read2st64_b32 v[224:225], v177 offset0:126 offset1:127
	ds_read2st64_b32 v[226:227], v177 offset0:186 offset1:187
	ds_read2st64_b32 v[228:229], v177 offset0:188 offset1:189
	ds_read2st64_b32 v[134:135], v177 offset0:190 offset1:191
	s_waitcnt lgkmcnt(6)
	v_fma_f32 v215, v231, v218, v216
	v_fmac_f32_e32 v217, v215, v219
	ds_write2st64_b32 v177, v215, v217 offset0:248 offset1:249
	s_waitcnt lgkmcnt(3)
	v_fma_f32 v215, v217, v220, v226
	v_fmac_f32_e32 v227, v215, v221
	ds_write2st64_b32 v177, v215, v227 offset0:250 offset1:251
	s_waitcnt lgkmcnt(3)
	v_fma_f32 v215, v227, v222, v228
	v_fmac_f32_e32 v229, v215, v223
	s_waitcnt lgkmcnt(2)
	v_fma_f32 v134, v229, v224, v134
	v_fmac_f32_e32 v135, v134, v225
	ds_write2st64_b32 v177, v215, v229 offset0:252 offset1:253
	ds_write2st64_b32 v177, v134, v135 offset0:254 offset1:255
	s_branch .LBB0_239

; #define LAS __attribute__((address_space(3)))
; __device__ __forceinline__ void lru_job(const bf16_t* P, bf16_t* Y, int l, int b, int kb, LAS float* lds, int wave_s) {
;     ...
;         for (int tt = 0; tt < 8; ++tt) { const int t = tg * 8 + tt; f32x2_t dd = {ba, bx};
; #pragma unroll
;             for (int i4 = 0; i4 < 16; ++i4) { const f32x4 xv = *(const LAS f32x4*)(XC + t * 64 + 4 * i4);
; #pragma unroll
;                 for (int q = 0; q < 4; ++q) { const f32x2_t xb = {xv[q], xv[q]}; dd = __builtin_elementwise_fma(xb, wax[4 * i4 + q], dd); } }
.LBB0_955:
	ds_read_b128 v[40:43], v99
	ds_read_b128 v[56:59], v99 offset:4096
	ds_read_b128 v[44:47], v99 offset:16
	ds_read_b128 v[60:63], v99 offset:4112
	ds_read_b128 v[48:51], v99 offset:32
	ds_read_b128 v[64:67], v99 offset:4128
	ds_read_b128 v[52:55], v99 offset:48
	ds_read_b128 v[68:71], v99 offset:4144
	ds_read_b32 v88, v100
	ds_read_b32 v89, v100 offset:256
	ds_read_b32 v90, v100 offset:512
	ds_read_b32 v91, v100 offset:768
	ds_read_b32 v92, v100 offset:4096
	ds_read_b32 v93, v100 offset:4352
	ds_read_b32 v94, v100 offset:4608
	ds_read_b32 v95, v100 offset:4864
	v_mov_b32_e32 v72, v96
	v_mov_b32_e32 v73, v96
	v_mov_b32_e32 v74, v96
	v_mov_b32_e32 v75, v96
	v_mov_b32_e32 v76, v97
	v_mov_b32_e32 v77, v97
	v_mov_b32_e32 v78, v97
	v_mov_b32_e32 v79, v97
	v_mov_b32_e32 v80, v96
	v_mov_b32_e32 v81, v96
	v_mov_b32_e32 v82, v96
	v_mov_b32_e32 v83, v96
	v_mov_b32_e32 v84, v97
	v_mov_b32_e32 v85, v97
	v_mov_b32_e32 v86, v97
	v_mov_b32_e32 v87, v97
	s_waitcnt lgkmcnt(14)
	s_nop 1
	v_mfma_f32_16x16x4_f32 v[72:75], v40, v0, v[72:75]
	v_mfma_f32_16x16x4_f32 v[76:79], v40, v16, v[76:79]
	v_mfma_f32_16x16x4_f32 v[80:83], v56, v0, v[80:83]
	v_mfma_f32_16x16x4_f32 v[84:87], v56, v16, v[84:87]
	v_mfma_f32_16x16x4_f32 v[72:75], v41, v1, v[72:75]
	v_mfma_f32_16x16x4_f32 v[76:79], v41, v17, v[76:79]
	v_mfma_f32_16x16x4_f32 v[80:83], v57, v1, v[80:83]
	v_mfma_f32_16x16x4_f32 v[84:87], v57, v17, v[84:87]
	v_mfma_f32_16x16x4_f32 v[72:75], v42, v2, v[72:75]
	v_mfma_f32_16x16x4_f32 v[76:79], v42, v18, v[76:79]
	v_mfma_f32_16x16x4_f32 v[80:83], v58, v2, v[80:83]
	v_mfma_f32_16x16x4_f32 v[84:87], v58, v18, v[84:87]
	v_mfma_f32_16x16x4_f32 v[72:75], v43, v3, v[72:75]
	v_mfma_f32_16x16x4_f32 v[76:79], v43, v19, v[76:79]
	v_mfma_f32_16x16x4_f32 v[80:83], v59, v3, v[80:83]
	v_mfma_f32_16x16x4_f32 v[84:87], v59, v19, v[84:87]
	s_waitcnt lgkmcnt(12)
	v_mfma_f32_16x16x4_f32 v[72:75], v44, v4, v[72:75]
	v_mfma_f32_16x16x4_f32 v[76:79], v44, v20, v[76:79]
	v_mfma_f32_16x16x4_f32 v[80:83], v60, v4, v[80:83]
	v_mfma_f32_16x16x4_f32 v[84:87], v60, v20, v[84:87]
	v_mfma_f32_16x16x4_f32 v[72:75], v45, v5, v[72:75]
	v_mfma_f32_16x16x4_f32 v[76:79], v45, v21, v[76:79]
	v_mfma_f32_16x16x4_f32 v[80:83], v61, v5, v[80:83]
	v_mfma_f32_16x16x4_f32 v[84:87], v61, v21, v[84:87]
	v_mfma_f32_16x16x4_f32 v[72:75], v46, v6, v[72:75]
	v_mfma_f32_16x16x4_f32 v[76:79], v46, v22, v[76:79]
	v_mfma_f32_16x16x4_f32 v[80:83], v62, v6, v[80:83]
	v_mfma_f32_16x16x4_f32 v[84:87], v62, v22, v[84:87]
	v_mfma_f32_16x16x4_f32 v[72:75], v47, v7, v[72:75]
	v_mfma_f32_16x16x4_f32 v[76:79], v47, v23, v[76:79]
	v_mfma_f32_16x16x4_f32 v[80:83], v63, v7, v[80:83]
	v_mfma_f32_16x16x4_f32 v[84:87], v63, v23, v[84:87]
	s_waitcnt lgkmcnt(10)
	v_mfma_f32_16x16x4_f32 v[72:75], v48, v8, v[72:75]
	v_mfma_f32_16x16x4_f32 v[76:79], v48, v24, v[76:79]
	v_mfma_f32_16x16x4_f32 v[80:83], v64, v8, v[80:83]
	v_mfma_f32_16x16x4_f32 v[84:87], v64, v24, v[84:87]
	v_mfma_f32_16x16x4_f32 v[72:75], v49, v9, v[72:75]
	v_mfma_f32_16x16x4_f32 v[76:79], v49, v25, v[76:79]
	v_mfma_f32_16x16x4_f32 v[80:83], v65, v9, v[80:83]
	v_mfma_f32_16x16x4_f32 v[84:87], v65, v25, v[84:87]
	v_mfma_f32_16x16x4_f32 v[72:75], v50, v10, v[72:75]
	v_mfma_f32_16x16x4_f32 v[76:79], v50, v26, v[76:79]
	v_mfma_f32_16x16x4_f32 v[80:83], v66, v10, v[80:83]
	v_mfma_f32_16x16x4_f32 v[84:87], v66, v26, v[84:87]
	v_mfma_f32_16x16x4_f32 v[72:75], v51, v11, v[72:75]
	v_mfma_f32_16x16x4_f32 v[76:79], v51, v27, v[76:79]
	v_mfma_f32_16x16x4_f32 v[80:83], v67, v11, v[80:83]
	v_mfma_f32_16x16x4_f32 v[84:87], v67, v27, v[84:87]
	s_waitcnt lgkmcnt(8)
	v_mfma_f32_16x16x4_f32 v[72:75], v52, v12, v[72:75]
	v_mfma_f32_16x16x4_f32 v[76:79], v52, v28, v[76:79]
	v_mfma_f32_16x16x4_f32 v[80:83], v68, v12, v[80:83]
	v_mfma_f32_16x16x4_f32 v[84:87], v68, v28, v[84:87]
	v_mfma_f32_16x16x4_f32 v[72:75], v53, v13, v[72:75]
	v_mfma_f32_16x16x4_f32 v[76:79], v53, v29, v[76:79]
	v_mfma_f32_16x16x4_f32 v[80:83], v69, v13, v[80:83]
	v_mfma_f32_16x16x4_f32 v[84:87], v69, v29, v[84:87]
	v_mfma_f32_16x16x4_f32 v[72:75], v54, v14, v[72:75]
	v_mfma_f32_16x16x4_f32 v[76:79], v54, v30, v[76:79]
	v_mfma_f32_16x16x4_f32 v[80:83], v70, v14, v[80:83]
	v_mfma_f32_16x16x4_f32 v[84:87], v70, v30, v[84:87]
	v_mfma_f32_16x16x4_f32 v[72:75], v55, v15, v[72:75]
	v_mfma_f32_16x16x4_f32 v[76:79], v55, v31, v[76:79]
	v_mfma_f32_16x16x4_f32 v[80:83], v71, v15, v[80:83]
	v_mfma_f32_16x16x4_f32 v[84:87], v71, v31, v[84:87]
	s_waitcnt lgkmcnt(0)
; __device__ __forceinline__ float sigmoidf_(float x) { return __builtin_amdgcn_rcpf(1.f + __expf(-x)); }
; __device__ __forceinline__ void lru_job(const bf16_t* P, bf16_t* Y, int l, int b, int kb, LAS float* lds, int wave_s) {
;     ...
;             const float rg = sigmoidf_(dd.x), ig = sigmoidf_(dd.y);
;             const float la = -8.f * rg * spl;
;             const float av = __expf(la);
;             Aa[t * 64 + j] = av;
;             Uu[t * 64 + j] = sqrtf(fmaxf(1.f - av * av, 0.f)) * (ig * XC[t * 64 + j]); }
;         __syncthreads();
	s_nop 7
	s_nop 3
	v_mul_f32_e32 v101, 0xbfb8aa3b, v72
	v_mul_f32_e32 v104, 0xbfb8aa3b, v73
	v_exp_f32_e32 v101, v101
	v_exp_f32_e32 v104, v104
	v_mul_f32_e32 v102, 0xbfb8aa3b, v76
	v_mul_f32_e32 v105, 0xbfb8aa3b, v77
	v_exp_f32_e32 v102, v102
	v_exp_f32_e32 v105, v105
	v_add_f32_e32 v101, 1.0, v101
	v_add_f32_e32 v104, 1.0, v104
	v_rcp_f32_e32 v101, v101
	v_rcp_f32_e32 v104, v104
	v_add_f32_e32 v102, 1.0, v102
	v_add_f32_e32 v105, 1.0, v105
	v_rcp_f32_e32 v102, v102
	v_rcp_f32_e32 v105, v105
	v_mul_f32_e32 v101, 0xc1000000, v101
	v_mul_f32_e32 v104, 0xc1000000, v104
	v_mul_f32_e32 v101, v98, v101
	v_mul_f32_e32 v104, v98, v104
	v_mul_f32_e32 v101, 0x3fb8aa3b, v101
	v_mul_f32_e32 v104, 0x3fb8aa3b, v104
	v_exp_f32_e32 v101, v101
	v_exp_f32_e32 v104, v104
	v_mul_f32_e32 v102, v88, v102
	v_mul_f32_e32 v105, v89, v105
	v_fma_f32 v103, -v101, v101, 1.0
	v_fma_f32 v106, -v104, v104, 1.0
	v_max_f32_e32 v103, 0, v103
	v_max_f32_e32 v106, 0, v106
	v_sqrt_f32_e32 v103, v103
	v_sqrt_f32_e32 v106, v106
	s_nop 0
	s_nop 0
	v_mul_f32_e32 v102, v102, v103
	v_mul_f32_e32 v105, v105, v106
	ds_write2st64_b32 v100, v101, v102 offset0:64 offset1:128
	ds_write2st64_b32 v100, v104, v105 offset0:65 offset1:129
	v_mul_f32_e32 v101, 0xbfb8aa3b, v74
	v_mul_f32_e32 v104, 0xbfb8aa3b, v75
	v_exp_f32_e32 v101, v101
	v_exp_f32_e32 v104, v104
	v_mul_f32_e32 v102, 0xbfb8aa3b, v78
	v_mul_f32_e32 v105, 0xbfb8aa3b, v79
	v_exp_f32_e32 v102, v102
	v_exp_f32_e32 v105, v105
	v_add_f32_e32 v101, 1.0, v101
	v_add_f32_e32 v104, 1.0, v104
	v_rcp_f32_e32 v101, v101
	v_rcp_f32_e32 v104, v104
	v_add_f32_e32 v102, 1.0, v102
	v_add_f32_e32 v105, 1.0, v105
	v_rcp_f32_e32 v102, v102
	v_rcp_f32_e32 v105, v105
	v_mul_f32_e32 v101, 0xc1000000, v101
	v_mul_f32_e32 v104, 0xc1000000, v104
	v_mul_f32_e32 v101, v98, v101
	v_mul_f32_e32 v104, v98, v104
	v_mul_f32_e32 v101, 0x3fb8aa3b, v101
	v_mul_f32_e32 v104, 0x3fb8aa3b, v104
	v_exp_f32_e32 v101, v101
	v_exp_f32_e32 v104, v104
	v_mul_f32_e32 v102, v90, v102
	v_mul_f32_e32 v105, v91, v105
	v_fma_f32 v103, -v101, v101, 1.0
	v_fma_f32 v106, -v104, v104, 1.0
	v_max_f32_e32 v103, 0, v103
	v_max_f32_e32 v106, 0, v106
	v_sqrt_f32_e32 v103, v103
	v_sqrt_f32_e32 v106, v106
	s_nop 0
	s_nop 0
	v_mul_f32_e32 v102, v102, v103
	v_mul_f32_e32 v105, v105, v106
	ds_write2st64_b32 v100, v101, v102 offset0:66 offset1:130
	ds_write2st64_b32 v100, v104, v105 offset0:67 offset1:131
	v_mul_f32_e32 v101, 0xbfb8aa3b, v80
	v_mul_f32_e32 v104, 0xbfb8aa3b, v81
	v_exp_f32_e32 v101, v101
	v_exp_f32_e32 v104, v104
	v_mul_f32_e32 v102, 0xbfb8aa3b, v84
	v_mul_f32_e32 v105, 0xbfb8aa3b, v85
	v_exp_f32_e32 v102, v102
	v_exp_f32_e32 v105, v105
	v_add_f32_e32 v101, 1.0, v101
	v_add_f32_e32 v104, 1.0, v104
	v_rcp_f32_e32 v101, v101
	v_rcp_f32_e32 v104, v104
	v_add_f32_e32 v102, 1.0, v102
	v_add_f32_e32 v105, 1.0, v105
	v_rcp_f32_e32 v102, v102
	v_rcp_f32_e32 v105, v105
	v_mul_f32_e32 v101, 0xc1000000, v101
	v_mul_f32_e32 v104, 0xc1000000, v104
	v_mul_f32_e32 v101, v98, v101
	v_mul_f32_e32 v104, v98, v104
	v_mul_f32_e32 v101, 0x3fb8aa3b, v101
	v_mul_f32_e32 v104, 0x3fb8aa3b, v104
	v_exp_f32_e32 v101, v101
	v_exp_f32_e32 v104, v104
	v_mul_f32_e32 v102, v92, v102
	v_mul_f32_e32 v105, v93, v105
	v_fma_f32 v103, -v101, v101, 1.0
	v_fma_f32 v106, -v104, v104, 1.0
	v_max_f32_e32 v103, 0, v103
	v_max_f32_e32 v106, 0, v106
	v_sqrt_f32_e32 v103, v103
	v_sqrt_f32_e32 v106, v106
	s_nop 0
	s_nop 0
	v_mul_f32_e32 v102, v102, v103
	v_mul_f32_e32 v105, v105, v106
	ds_write2st64_b32 v100, v101, v102 offset0:80 offset1:144
	ds_write2st64_b32 v100, v104, v105 offset0:81 offset1:145
	v_mul_f32_e32 v101, 0xbfb8aa3b, v82
	v_mul_f32_e32 v104, 0xbfb8aa3b, v83
	v_exp_f32_e32 v101, v101
	v_exp_f32_e32 v104, v104
	v_mul_f32_e32 v102, 0xbfb8aa3b, v86
	v_mul_f32_e32 v105, 0xbfb8aa3b, v87
	v_exp_f32_e32 v102, v102
	v_exp_f32_e32 v105, v105
	v_add_f32_e32 v101, 1.0, v101
	v_add_f32_e32 v104, 1.0, v104
	v_rcp_f32_e32 v101, v101
	v_rcp_f32_e32 v104, v104
	v_add_f32_e32 v102, 1.0, v102
	v_add_f32_e32 v105, 1.0, v105
	v_rcp_f32_e32 v102, v102
	v_rcp_f32_e32 v105, v105
	v_mul_f32_e32 v101, 0xc1000000, v101
	v_mul_f32_e32 v104, 0xc1000000, v104
	v_mul_f32_e32 v101, v98, v101
	v_mul_f32_e32 v104, v98, v104
	v_mul_f32_e32 v101, 0x3fb8aa3b, v101
	v_mul_f32_e32 v104, 0x3fb8aa3b, v104
	v_exp_f32_e32 v101, v101
	v_exp_f32_e32 v104, v104
	v_mul_f32_e32 v102, v94, v102
	v_mul_f32_e32 v105, v95, v105
	v_fma_f32 v103, -v101, v101, 1.0
	v_fma_f32 v106, -v104, v104, 1.0
	v_max_f32_e32 v103, 0, v103
	v_max_f32_e32 v106, 0, v106
	v_sqrt_f32_e32 v103, v103
	v_sqrt_f32_e32 v106, v106
	s_nop 0
	s_nop 0
	v_mul_f32_e32 v102, v102, v103
	v_mul_f32_e32 v105, v105, v106
	ds_write2st64_b32 v100, v101, v102 offset0:82 offset1:146
	ds_write2st64_b32 v100, v104, v105 offset0:83 offset1:147
	s_waitcnt lgkmcnt(0)
	s_barrier
	s_and_saveexec_b64 s[4:5], vcc
	s_cbranch_execz .LBB0_952
; __device__ __forceinline__ void lru_job(const bf16_t* P, bf16_t* Y, int l, int b, int kb, LAS float* lds, int wave_s) {
;     ...
;         if (tid < 64) {
;             for (int tb = 0; tb < TC; tb += 8) { float av[8], uv[8];
; #pragma unroll
;                 for (int k = 0; k < 8; ++k) { av[k] = Aa[(tb + k) * 64 + j]; uv[k] = Uu[(tb + k) * 64 + j]; }
; #pragma unroll
;                 for (int k = 0; k < 8; ++k) { hs = av[k] * hs + uv[k]; Hh[(tb + k) * 64 + j] = hs; } }
;         }
	ds_read2st64_b32 v[216:217], v176 offset0:128 offset1:129
	ds_read2st64_b32 v[218:219], v176 offset0:64 offset1:65
	ds_read2st64_b32 v[220:221], v176 offset0:66 offset1:67
	ds_read2st64_b32 v[222:223], v176 offset0:68 offset1:69
	ds_read2st64_b32 v[224:225], v176 offset0:70 offset1:71
	ds_read2st64_b32 v[226:227], v176 offset0:130 offset1:131
	ds_read2st64_b32 v[228:229], v176 offset0:132 offset1:133
	ds_read2st64_b32 v[230:231], v176 offset0:134 offset1:135
	s_waitcnt lgkmcnt(6)
	v_fma_f32 v134, v135, v218, v216
	v_fmac_f32_e32 v217, v134, v219
	ds_write2st64_b32 v176, v134, v217 offset0:192 offset1:193
	s_waitcnt lgkmcnt(3)
	v_fma_f32 v134, v217, v220, v226
	v_fmac_f32_e32 v227, v134, v221
	ds_write2st64_b32 v176, v134, v227 offset0:194 offset1:195
	s_waitcnt lgkmcnt(3)
	v_fma_f32 v134, v227, v222, v228
	v_fmac_f32_e32 v229, v134, v223
	ds_write2st64_b32 v176, v134, v229 offset0:196 offset1:197
	s_waitcnt lgkmcnt(3)
	v_fma_f32 v134, v229, v224, v230
	v_fmac_f32_e32 v231, v134, v225
	ds_write2st64_b32 v176, v134, v231 offset0:198 offset1:199
	ds_read2st64_b32 v[134:135], v176 offset0:136 offset1:137
	ds_read2st64_b32 v[216:217], v176 offset0:72 offset1:73
	ds_read2st64_b32 v[218:219], v176 offset0:74 offset1:75
	ds_read2st64_b32 v[220:221], v176 offset0:76 offset1:77
	ds_read2st64_b32 v[222:223], v176 offset0:78 offset1:79
	ds_read2st64_b32 v[224:225], v176 offset0:138 offset1:139
	ds_read2st64_b32 v[226:227], v176 offset0:140 offset1:141
	ds_read2st64_b32 v[228:229], v176 offset0:142 offset1:143
	s_waitcnt lgkmcnt(6)
	v_fma_f32 v134, v231, v216, v134
	v_fmac_f32_e32 v135, v134, v217
	ds_write2st64_b32 v176, v134, v135 offset0:200 offset1:201
	s_waitcnt lgkmcnt(3)
	v_fma_f32 v134, v135, v218, v224
	v_fmac_f32_e32 v225, v134, v219
	ds_write2st64_b32 v176, v134, v225 offset0:202 offset1:203
	s_waitcnt lgkmcnt(3)
	v_fma_f32 v134, v225, v220, v226
	v_fmac_f32_e32 v227, v134, v221
	ds_write2st64_b32 v176, v134, v227 offset0:204 offset1:205
	s_waitcnt lgkmcnt(3)
	v_fma_f32 v134, v227, v222, v228
	v_fmac_f32_e32 v229, v134, v223
	ds_write2st64_b32 v176, v134, v229 offset0:206 offset1:207
	ds_read2st64_b32 v[134:135], v176 offset0:144 offset1:145
	ds_read2st64_b32 v[216:217], v176 offset0:80 offset1:81
	ds_read2st64_b32 v[218:219], v176 offset0:82 offset1:83
	ds_read2st64_b32 v[220:221], v176 offset0:84 offset1:85
	ds_read2st64_b32 v[222:223], v176 offset0:86 offset1:87
	ds_read2st64_b32 v[224:225], v176 offset0:146 offset1:147
	ds_read2st64_b32 v[226:227], v176 offset0:148 offset1:149
	ds_read2st64_b32 v[230:231], v176 offset0:150 offset1:151
	s_waitcnt lgkmcnt(6)
	v_fma_f32 v134, v229, v216, v134
	v_fmac_f32_e32 v135, v134, v217
	ds_write2st64_b32 v176, v134, v135 offset0:208 offset1:209
	s_waitcnt lgkmcnt(3)
	v_fma_f32 v134, v135, v218, v224
	v_fmac_f32_e32 v225, v134, v219
	ds_write2st64_b32 v176, v134, v225 offset0:210 offset1:211
	s_waitcnt lgkmcnt(3)
	v_fma_f32 v134, v225, v220, v226
	v_fmac_f32_e32 v227, v134, v221
	ds_write2st64_b32 v176, v134, v227 offset0:212 offset1:213
	s_waitcnt lgkmcnt(3)
	v_fma_f32 v134, v227, v222, v230
	v_fmac_f32_e32 v231, v134, v223
	ds_write2st64_b32 v176, v134, v231 offset0:214 offset1:215
	ds_read2st64_b32 v[134:135], v176 offset0:152 offset1:153
	ds_read2st64_b32 v[216:217], v176 offset0:88 offset1:89
	ds_read2st64_b32 v[218:219], v176 offset0:90 offset1:91
	ds_read2st64_b32 v[220:221], v176 offset0:92 offset1:93
	ds_read2st64_b32 v[222:223], v176 offset0:94 offset1:95
	ds_read2st64_b32 v[224:225], v176 offset0:154 offset1:155
	ds_read2st64_b32 v[226:227], v176 offset0:156 offset1:157
	ds_read2st64_b32 v[228:229], v176 offset0:158 offset1:159
	s_waitcnt lgkmcnt(6)
	v_fma_f32 v134, v231, v216, v134
	v_fmac_f32_e32 v135, v134, v217
	ds_write2st64_b32 v176, v134, v135 offset0:216 offset1:217
	s_waitcnt lgkmcnt(3)
	v_fma_f32 v134, v135, v218, v224
	v_fmac_f32_e32 v225, v134, v219
	ds_write2st64_b32 v176, v134, v225 offset0:218 offset1:219
	s_waitcnt lgkmcnt(3)
	v_fma_f32 v134, v225, v220, v226
	v_fmac_f32_e32 v227, v134, v221
	ds_write2st64_b32 v176, v134, v227 offset0:220 offset1:221
	s_waitcnt lgkmcnt(3)
; __device__ __forceinline__ void lru_job(const bf16_t* P, bf16_t* Y, int l, int b, int kb, LAS float* lds, int wave_s) {
;     ...
;         if (tid < 64) {
;             for (int tb = 0; tb < TC; tb += 8) { float av[8], uv[8];
; #pragma unroll
;                 for (int k = 0; k < 8; ++k) { av[k] = Aa[(tb + k) * 64 + j]; uv[k] = Uu[(tb + k) * 64 + j]; }
; #pragma unroll
;                 for (int k = 0; k < 8; ++k) { hs = av[k] * hs + uv[k]; Hh[(tb + k) * 64 + j] = hs; } }
;         }
	v_fma_f32 v134, v227, v222, v228
	v_fmac_f32_e32 v229, v134, v223
	ds_write2st64_b32 v176, v134, v229 offset0:222 offset1:223
	ds_read2st64_b32 v[134:135], v176 offset0:160 offset1:161
	ds_read2st64_b32 v[216:217], v176 offset0:96 offset1:97
	ds_read2st64_b32 v[218:219], v176 offset0:98 offset1:99
	ds_read2st64_b32 v[220:221], v176 offset0:100 offset1:101
	ds_read2st64_b32 v[222:223], v176 offset0:102 offset1:103
	ds_read2st64_b32 v[224:225], v176 offset0:162 offset1:163
	ds_read2st64_b32 v[226:227], v176 offset0:164 offset1:165
	ds_read2st64_b32 v[230:231], v176 offset0:166 offset1:167
	s_waitcnt lgkmcnt(6)
	v_fma_f32 v134, v229, v216, v134
	v_fmac_f32_e32 v135, v134, v217
	ds_write2st64_b32 v176, v134, v135 offset0:224 offset1:225
	s_waitcnt lgkmcnt(3)
	v_fma_f32 v134, v135, v218, v224
	v_fmac_f32_e32 v225, v134, v219
	ds_write2st64_b32 v176, v134, v225 offset0:226 offset1:227
	s_waitcnt lgkmcnt(3)
	v_fma_f32 v134, v225, v220, v226
	v_fmac_f32_e32 v227, v134, v221
	ds_write2st64_b32 v176, v134, v227 offset0:228 offset1:229
	s_waitcnt lgkmcnt(3)
	v_fma_f32 v134, v227, v222, v230
	v_fmac_f32_e32 v231, v134, v223
	ds_write2st64_b32 v176, v134, v231 offset0:230 offset1:231
	ds_read2st64_b32 v[134:135], v176 offset0:168 offset1:169
	ds_read2st64_b32 v[216:217], v176 offset0:104 offset1:105
	ds_read2st64_b32 v[218:219], v176 offset0:106 offset1:107
	ds_read2st64_b32 v[220:221], v176 offset0:108 offset1:109
	ds_read2st64_b32 v[222:223], v176 offset0:110 offset1:111
	ds_read2st64_b32 v[224:225], v176 offset0:170 offset1:171
	ds_read2st64_b32 v[226:227], v176 offset0:172 offset1:173
	ds_read2st64_b32 v[228:229], v176 offset0:174 offset1:175
	s_waitcnt lgkmcnt(6)
	v_fma_f32 v134, v231, v216, v134
	v_fmac_f32_e32 v135, v134, v217
	ds_write2st64_b32 v176, v134, v135 offset0:232 offset1:233
	s_waitcnt lgkmcnt(3)
	v_fma_f32 v134, v135, v218, v224
	v_fmac_f32_e32 v225, v134, v219
	ds_write2st64_b32 v176, v134, v225 offset0:234 offset1:235
	s_waitcnt lgkmcnt(3)
	v_fma_f32 v134, v225, v220, v226
	v_fmac_f32_e32 v227, v134, v221
	ds_write2st64_b32 v176, v134, v227 offset0:236 offset1:237
	s_waitcnt lgkmcnt(3)
	v_fma_f32 v134, v227, v222, v228
	v_fmac_f32_e32 v229, v134, v223
	ds_write2st64_b32 v176, v134, v229 offset0:238 offset1:239
	ds_read2st64_b32 v[134:135], v176 offset0:176 offset1:177
	ds_read2st64_b32 v[216:217], v176 offset0:112 offset1:113
	ds_read2st64_b32 v[218:219], v176 offset0:114 offset1:115
	ds_read2st64_b32 v[220:221], v176 offset0:116 offset1:117
	ds_read2st64_b32 v[222:223], v176 offset0:118 offset1:119
	ds_read2st64_b32 v[224:225], v176 offset0:178 offset1:179
	ds_read2st64_b32 v[226:227], v176 offset0:180 offset1:181
	ds_read2st64_b32 v[230:231], v176 offset0:182 offset1:183
	s_waitcnt lgkmcnt(6)
	v_fma_f32 v134, v229, v216, v134
	v_fmac_f32_e32 v135, v134, v217
	ds_write2st64_b32 v176, v134, v135 offset0:240 offset1:241
	s_waitcnt lgkmcnt(3)
	v_fma_f32 v134, v135, v218, v224
	v_fmac_f32_e32 v225, v134, v219
	ds_write2st64_b32 v176, v134, v225 offset0:242 offset1:243
	s_waitcnt lgkmcnt(3)
	v_fma_f32 v134, v225, v220, v226
	v_fmac_f32_e32 v227, v134, v221
	ds_write2st64_b32 v176, v134, v227 offset0:244 offset1:245
	s_waitcnt lgkmcnt(3)
	v_fma_f32 v134, v227, v222, v230
	v_fmac_f32_e32 v231, v134, v223
	ds_write2st64_b32 v176, v134, v231 offset0:246 offset1:247
	ds_read2st64_b32 v[216:217], v176 offset0:184 offset1:185
	ds_read2st64_b32 v[218:219], v176 offset0:120 offset1:121
	ds_read2st64_b32 v[220:221], v176 offset0:122 offset1:123
	ds_read2st64_b32 v[222:223], v176 offset0:124 offset1:125
	ds_read2st64_b32 v[224:225], v176 offset0:126 offset1:127
	ds_read2st64_b32 v[226:227], v176 offset0:186 offset1:187
	ds_read2st64_b32 v[228:229], v176 offset0:188 offset1:189
	ds_read2st64_b32 v[134:135], v176 offset0:190 offset1:191
	s_waitcnt lgkmcnt(6)
	v_fma_f32 v216, v231, v218, v216
	v_fmac_f32_e32 v217, v216, v219
	ds_write2st64_b32 v176, v216, v217 offset0:248 offset1:249
	s_waitcnt lgkmcnt(3)
	v_fma_f32 v216, v217, v220, v226
	v_fmac_f32_e32 v227, v216, v221
	ds_write2st64_b32 v176, v216, v227 offset0:250 offset1:251
	s_waitcnt lgkmcnt(3)
	v_fma_f32 v216, v227, v222, v228
	v_fmac_f32_e32 v229, v216, v223
	s_waitcnt lgkmcnt(2)
	v_fma_f32 v134, v229, v224, v134
	v_fmac_f32_e32 v135, v134, v225
	ds_write2st64_b32 v176, v216, v229 offset0:252 offset1:253
	ds_write2st64_b32 v176, v134, v135 offset0:254 offset1:255
	s_branch .LBB0_952
